# diff-attn diagonal tiles: bias-table reads batched and unconditional (table is padded for it), add + select instead of 16 predicated reads each with its own lgkmcnt(0) and exec diamond
# speedup vs baseline: 1.0070x; 1.0070x over previous
; __device__ __forceinline__ void bias_mask_tile(f32x16& p0, f32x16& p1, int dq, unsigned W, const float* tbx) {
;     const float NEG = -__builtin_inff();
;     const float* bp = tbx + (dq - 63);
; #pragma unroll
;     for (int r = 0; r < 16; ++r) {
;         const int c = (r & 3) + 8 * (r >> 2);
;         const unsigned r0 = (unsigned)(dq - c), r1 = (unsigned)(dq - c - 32);
;         const float b0 = bp[63 - c], b1 = bp[31 - c];
;         p0[r] = r0 >= W ? NEG : p0[r] + b0;
;         p1[r] = r1 >= W ? NEG : p1[r] + b1;
;         if ((r & 3) == 3) __builtin_amdgcn_sched_barrier(0);
;     }
; }
.LBB0_451:
	s_cmp_le_u32 s90, s79
	s_cbranch_scc1 .LBB0_485
	ds_read_b32 v176, v247 offset:236
	ds_read_b32 v177, v247 offset:232
	ds_read_b32 v178, v247 offset:228
	ds_read_b32 v179, v247 offset:224
	ds_read_b32 v180, v247 offset:204
	ds_read_b32 v181, v247 offset:200
	ds_read_b32 v182, v247 offset:196
	ds_read_b32 v183, v247 offset:192
	ds_read_b32 v184, v247 offset:172
	ds_read_b32 v185, v247 offset:168
	ds_read_b32 v186, v247 offset:164
	ds_read_b32 v187, v247 offset:160
	ds_read_b32 v188, v247 offset:140
	ds_read_b32 v189, v247 offset:136
	ds_read_b32 v190, v247 offset:132
	ds_read_b32 v191, v247 offset:128
	s_waitcnt lgkmcnt(0)
	v_add_u32_e32 v0, 59, v248
	v_cmp_gt_u32_e32 vcc, 2.0, v0
	v_add_f32_e32 v160, v160, v176
	v_add_u32_e32 v2, 58, v248
	v_cndmask_b32_e32 v160, v235, v160, vcc
	v_cmp_gt_u32_e32 vcc, 2.0, v2
	v_add_f32_e32 v161, v161, v177
	v_add_u32_e32 v0, 57, v248
	v_cndmask_b32_e32 v161, v235, v161, vcc
	v_cmp_gt_u32_e32 vcc, 2.0, v0
	v_add_f32_e32 v162, v162, v178
	v_add_u32_e32 v2, 56, v248
	v_cndmask_b32_e32 v162, v235, v162, vcc
	v_cmp_gt_u32_e32 vcc, 2.0, v2
	v_add_f32_e32 v163, v163, v179
	v_add_u32_e32 v0, 51, v248
	v_cndmask_b32_e32 v163, v235, v163, vcc
	v_cmp_gt_u32_e32 vcc, 2.0, v0
	v_add_f32_e32 v164, v164, v180
	v_add_u32_e32 v2, 50, v248
	v_cndmask_b32_e32 v164, v235, v164, vcc
	v_cmp_gt_u32_e32 vcc, 2.0, v2
	v_add_f32_e32 v165, v165, v181
	v_add_u32_e32 v0, 49, v248
	v_cndmask_b32_e32 v165, v235, v165, vcc
	v_cmp_gt_u32_e32 vcc, 2.0, v0
	v_add_f32_e32 v166, v166, v182
	v_add_u32_e32 v2, 48, v248
	v_cndmask_b32_e32 v166, v235, v166, vcc
	v_cmp_gt_u32_e32 vcc, 2.0, v2
	v_add_f32_e32 v167, v167, v183
	v_add_u32_e32 v0, 43, v248
	v_cndmask_b32_e32 v167, v235, v167, vcc
	v_cmp_gt_u32_e32 vcc, 2.0, v0
	v_add_f32_e32 v168, v168, v184
	v_add_u32_e32 v2, 42, v248
	v_cndmask_b32_e32 v168, v235, v168, vcc
	v_cmp_gt_u32_e32 vcc, 2.0, v2
	v_add_f32_e32 v169, v169, v185
	v_add_u32_e32 v0, 41, v248
	v_cndmask_b32_e32 v169, v235, v169, vcc
	v_cmp_gt_u32_e32 vcc, 2.0, v0
	v_add_f32_e32 v170, v170, v186
	v_add_u32_e32 v2, 40, v248
	v_cndmask_b32_e32 v170, v235, v170, vcc
	v_cmp_gt_u32_e32 vcc, 2.0, v2
	v_add_f32_e32 v171, v171, v187
	v_add_u32_e32 v0, 35, v248
	v_cndmask_b32_e32 v171, v235, v171, vcc
	v_cmp_gt_u32_e32 vcc, 2.0, v0
	v_add_f32_e32 v172, v172, v188
	v_add_u32_e32 v2, 34, v248
	v_cndmask_b32_e32 v172, v235, v172, vcc
	v_cmp_gt_u32_e32 vcc, 2.0, v2
	v_add_f32_e32 v173, v173, v189
	v_add_u32_e32 v0, 33, v248
	v_cndmask_b32_e32 v173, v235, v173, vcc
	v_cmp_gt_u32_e32 vcc, 2.0, v0
	v_add_f32_e32 v174, v174, v190
	v_add_u32_e32 v2, 32, v248
	v_cndmask_b32_e32 v174, v235, v174, vcc
	v_cmp_gt_u32_e32 vcc, 2.0, v2
	v_add_f32_e32 v175, v175, v191
	s_nop 0
	v_cndmask_b32_e32 v175, v235, v175, vcc
	ds_read_b32 v176, v247 offset:108
	ds_read_b32 v177, v247 offset:104
	ds_read_b32 v178, v247 offset:100
	ds_read_b32 v179, v247 offset:96
	ds_read_b32 v180, v247 offset:76
	ds_read_b32 v181, v247 offset:72
	ds_read_b32 v182, v247 offset:68
	ds_read_b32 v183, v247 offset:64
	ds_read_b32 v184, v247 offset:44
	ds_read_b32 v185, v247 offset:40
	ds_read_b32 v186, v247 offset:36
	ds_read_b32 v187, v247 offset:32
	ds_read_b32 v188, v247 offset:12
	ds_read_b32 v189, v247 offset:8
	ds_read_b32 v190, v247 offset:4
	ds_read_b32 v191, v247
	s_waitcnt lgkmcnt(0)
	v_add_u32_e32 v0, 27, v248
	v_cmp_gt_u32_e32 vcc, 2.0, v0
	v_add_f32_e32 v144, v144, v176
	v_add_u32_e32 v2, 26, v248
	v_cndmask_b32_e32 v144, v235, v144, vcc
	v_cmp_gt_u32_e32 vcc, 2.0, v2
	v_add_f32_e32 v145, v145, v177
	v_add_u32_e32 v0, 25, v248
	v_cndmask_b32_e32 v145, v235, v145, vcc
	v_cmp_gt_u32_e32 vcc, 2.0, v0
	v_add_f32_e32 v146, v146, v178
	v_add_u32_e32 v2, 24, v248
	v_cndmask_b32_e32 v146, v235, v146, vcc
	v_cmp_gt_u32_e32 vcc, 2.0, v2
	v_add_f32_e32 v147, v147, v179
	v_add_u32_e32 v0, 19, v248
	v_cndmask_b32_e32 v147, v235, v147, vcc
	v_cmp_gt_u32_e32 vcc, 2.0, v0
	v_add_f32_e32 v148, v148, v180
	v_add_u32_e32 v2, 18, v248
	v_cndmask_b32_e32 v148, v235, v148, vcc
	v_cmp_gt_u32_e32 vcc, 2.0, v2
	v_add_f32_e32 v149, v149, v181
	v_add_u32_e32 v0, 17, v248
	v_cndmask_b32_e32 v149, v235, v149, vcc
	v_cmp_gt_u32_e32 vcc, 2.0, v0
	v_add_f32_e32 v150, v150, v182
	v_add_u32_e32 v2, 16, v248
	v_cndmask_b32_e32 v150, v235, v150, vcc
	v_cmp_gt_u32_e32 vcc, 2.0, v2
	v_add_f32_e32 v151, v151, v183
	v_add_u32_e32 v0, 11, v248
	v_cndmask_b32_e32 v151, v235, v151, vcc
	v_cmp_gt_u32_e32 vcc, 2.0, v0
	v_add_f32_e32 v152, v152, v184
	v_add_u32_e32 v2, 10, v248
	v_cndmask_b32_e32 v152, v235, v152, vcc
	v_cmp_gt_u32_e32 vcc, 2.0, v2
	v_add_f32_e32 v153, v153, v185
	v_add_u32_e32 v0, 9, v248
	v_cndmask_b32_e32 v153, v235, v153, vcc
	v_cmp_gt_u32_e32 vcc, 2.0, v0
	v_add_f32_e32 v154, v154, v186
	v_add_u32_e32 v2, 8, v248
	v_cndmask_b32_e32 v154, v235, v154, vcc
	v_cmp_gt_u32_e32 vcc, 2.0, v2
	v_add_f32_e32 v155, v155, v187
	v_add_u32_e32 v0, 3, v248
	v_cndmask_b32_e32 v155, v235, v155, vcc
	v_cmp_gt_u32_e32 vcc, 2.0, v0
	v_add_f32_e32 v156, v156, v188
	v_add_u32_e32 v2, 2, v248
	v_cndmask_b32_e32 v156, v235, v156, vcc
	v_cmp_gt_u32_e32 vcc, 2.0, v2
	v_add_f32_e32 v157, v157, v189
	v_add_u32_e32 v0, 1, v248
	v_cndmask_b32_e32 v157, v235, v157, vcc
	v_cmp_gt_u32_e32 vcc, 2.0, v0
	v_add_f32_e32 v158, v158, v190
	v_add_u32_e32 v2, 0, v248
	v_cndmask_b32_e32 v158, v235, v158, vcc
	v_cmp_gt_u32_e32 vcc, 2.0, v2
	v_add_f32_e32 v159, v159, v191
	s_nop 0
	v_cndmask_b32_e32 v159, v235, v159, vcc
